# in-proj GEMM tile order: column-tile index rotated by 8 so no workgroup gets three heavy-epilogue (hf/dk/dv f32-output) tiles
# speedup vs baseline: 1.0128x; 1.0080x over previous
.LBB0_134:
	s_load_dwordx16 s[4:19], s[0:1], 0x70
	s_cmp_lt_i32 s44, 2
	s_cselect_b64 s[0:1], -1, 0
	s_cmp_gt_i32 s45, 1
	s_cselect_b64 s[2:3], -1, 0
	s_waitcnt lgkmcnt(0)
	v_writelane_b32 v254, s4, 28
	s_and_b64 s[0:1], s[0:1], s[2:3]
	s_andn2_b64 vcc, exec, s[0:1]
	v_writelane_b32 v254, s5, 29
	v_writelane_b32 v254, s6, 30
	v_writelane_b32 v254, s7, 31
	v_writelane_b32 v254, s8, 32
	v_writelane_b32 v254, s9, 33
	v_writelane_b32 v254, s10, 34
	v_writelane_b32 v254, s11, 35
	v_writelane_b32 v254, s12, 36
	v_writelane_b32 v254, s13, 37
	v_writelane_b32 v254, s14, 38
	v_writelane_b32 v254, s15, 39
	v_writelane_b32 v254, s16, 40
	v_writelane_b32 v254, s17, 41
	v_writelane_b32 v254, s18, 42
	v_writelane_b32 v254, s19, 43
	v_writelane_b32 v254, s84, 44
	s_mov_b64 s[0:1], s[44:45]
	s_mov_b32 s2, s46
	v_writelane_b32 v254, s85, 45
	v_writelane_b32 v254, s86, 46
	v_writelane_b32 v254, s87, 47
	v_writelane_b32 v254, s88, 48
	v_writelane_b32 v254, s89, 49
	v_writelane_b32 v254, s90, 50
	v_writelane_b32 v254, s91, 51
	v_writelane_b32 v254, s0, 52
	s_nop 1
	v_writelane_b32 v254, s1, 53
	v_writelane_b32 v254, s2, 54
	v_writelane_b32 v254, s3, 55
	v_writelane_b32 v254, s43, 56
	s_cbranch_vccnz .LBB0_671
	s_cmpk_lt_i32 s43, 0x5ac
	s_cselect_b64 s[2:3], -1, 0
	s_cmpk_gt_i32 s43, 0x5ab
	v_readfirstlane_b32 s8, v0
	s_cbranch_scc1 .LBB0_137
	s_ashr_i32 s0, s43, 31
	s_lshr_b32 s0, s0, 29
	s_add_i32 s0, s43, s0
	s_and_b32 s1, s0, -8
	s_sub_i32 s1, s43, s1
	s_mul_i32 s5, s1, 0xb5
	s_add_i32 s5, s5, 4
	s_ashr_i32 s0, s0, 3
	s_mul_i32 s4, s1, 0xb6
	s_cmp_lt_i32 s1, 4
	s_cselect_b32 s1, s4, s5
	s_add_i32 s1, s1, s0
	s_mul_hi_i32 s0, s1, 0x2e8ba2e9
	s_lshr_b32 s4, s0, 31
	s_ashr_i32 s0, s0, 6
	s_add_i32 s0, s0, s4
	s_lshl_b32 s4, s0, 3
	s_sub_i32 s5, 33, s4
	s_mulk_i32 s0, 0x160
	s_min_u32 s5, s5, 8
	s_sub_i32 s6, s1, s0
	s_sext_i32_i16 s0, s6
	v_cvt_f32_ubyte0_e32 v2, s5
	v_cvt_f32_i32_e32 v1, s0
	v_rcp_iflag_f32_e32 v3, v2
	s_ashr_i32 s0, s0, 30
	s_or_b32 s7, s0, 1
	v_mul_f32_e32 v3, v1, v3
	v_trunc_f32_e32 v3, v3
	v_fma_f32 v1, -v3, v2, v1
	v_cvt_i32_f32_e32 v3, v3
	v_cmp_ge_f32_e64 s[0:1], |v1|, v2
	s_and_b64 s[0:1], s[0:1], exec
	s_cselect_b32 s0, s7, 0
	v_readfirstlane_b32 s1, v3
	s_add_i32 s1, s1, s0
	s_sext_i32_i16 s0, s1
	s_mul_i32 s1, s1, s5
	s_sub_i32 s1, s6, s1
	s_sext_i32_i16 s1, s1
	s_add_i32 s4, s4, s1
	s_add_i32 s1, s0, -36
	s_add_i32 s0, s0, 8
	s_cmp_gt_i32 s0, 43
	s_cselect_b32 s0, s1, s0

.LBB0_148:
	s_ashr_i32 s1, s1, 3
	s_add_i32 s1, s22, s1
	s_mul_hi_i32 s5, s1, 0x2e8ba2e9
	s_lshr_b32 s20, s5, 31
	s_ashr_i32 s5, s5, 6
	s_add_i32 s5, s5, s20
	s_lshl_b32 s21, s5, 3
	s_sub_i32 s20, 33, s21
	s_min_i32 s22, s20, 8
	s_abs_i32 s20, s22
	v_cvt_f32_u32_e32 v2, s20
	s_sub_i32 s24, 0, s20
	s_mulk_i32 s5, 0x160
	s_sub_i32 s1, s1, s5
	v_rcp_iflag_f32_e32 v2, v2
	s_abs_i32 s5, s1
	s_xor_b32 s23, s1, s22
	s_ashr_i32 s23, s23, 31
	v_mul_f32_e32 v2, 0x4f7ffffe, v2
	v_cvt_u32_f32_e32 v2, v2
	s_nop 0
	v_readfirstlane_b32 s25, v2
	s_mul_i32 s24, s24, s25
	s_mul_hi_u32 s24, s25, s24
	s_add_i32 s25, s25, s24
	s_mul_hi_u32 s24, s5, s25
	s_mul_i32 s25, s24, s20
	s_sub_i32 s5, s5, s25
	s_add_i32 s26, s24, 1
	s_sub_i32 s25, s5, s20
	s_cmp_ge_u32 s5, s20
	s_cselect_b32 s24, s26, s24
	s_cselect_b32 s5, s25, s5
	s_add_i32 s25, s24, 1
	s_cmp_ge_u32 s5, s20
	s_cselect_b32 s5, s25, s24
	s_xor_b32 s5, s5, s23
	s_sub_i32 s20, s5, s23
	s_mul_i32 s5, s20, s22
	s_sub_i32 s1, s1, s5
	s_add_i32 s22, s21, s1
	s_add_i32 s5, s20, -36
	s_add_i32 s20, s20, 8
	s_cmp_gt_i32 s20, 43
	s_cselect_b32 s20, s5, s20
